# combined: attention epilogue stores widened to 16 B through a per-wave LDS transpose, loop back-edge rotated in front of the barrier, k-scaled weight transposes issue their loads in batches, redundant
# speedup vs baseline: 1.0113x; 1.0006x over previous
; __device__ __forceinline__ int crow(int r, int hi) { return (r & 3) + 8 * (r >> 2) + 4 * hi; }
; __device__ __forceinline__ unsigned cvtpk(float lo, float hi) { unsigned r; asm volatile("v_cvt_pk_bf16_f32 %0, %1, %2" : "=v"(r) : "v"(lo), "v"(hi)); return r; }
; __device__ __forceinline__ void attn_unit(const bf16_t* __restrict__ Qb, const bf16_t* __restrict__ KNh, const bf16_t* __restrict__ KRb, const bf16_t* __restrict__ Vh,
;                                           bf16_t* __restrict__ Ob, int nkeys, char* lds, int tid_in) {
;     ...
;   { auto rr = __builtin_amdgcn_permlane32_swap(__float_as_uint(l_reg), __float_as_uint(l_reg), false, false); l_reg = __uint_as_float(rr[0]) + __uint_as_float(rr[1]); }
;   if (hi == 0) li_l[r32] = l_reg;
;   asm volatile("s_waitcnt lgkmcnt(0)" ::: "memory");
;   float rli[16];
; #pragma unroll
;   for (int r = 0; r < 16; ++r) rli[r] = __builtin_amdgcn_rcpf(li_l[crow(r, hi)]);
;   bf16_t* Ow = Ob + (long)(wid * QBLK) * 1024;
; #pragma unroll
;   for (int r = 0; r < 16; ++r) { int orow = crow(r, hi);
; #pragma unroll
;     for (int d0 = 0; d0 < 2; ++d0) { const float v = o[d0][r] * rli[r]; Ow[(long)orow * 1024 + d0 * 32 + r32] = (bf16_t)(cvtpk(v, v) & 0xffffu); } }
;   __syncthreads();
.LBB0_231:
	s_or_b64 exec, exec, s[18:19]
	s_waitcnt lgkmcnt(0)
	ds_read_b128 v[34:37], v179 offset:51200
	ds_read_b128 v[38:41], v179 offset:51232
	ds_read_b128 v[54:57], v179 offset:51264
	ds_read_b128 v[58:61], v179 offset:51296
	s_lshl_b64 s[18:19], s[24:25], 11
	s_add_u32 s18, s94, s18
	s_addc_u32 s19, s95, s19
	s_lshl_b32 s24, s36, 7
	s_add_u32 s18, s18, s24
	s_addc_u32 s19, s19, 0
	v_mul_u32_u24_e32 v62, 0x90, v178
	v_mul_u32_u24_e32 v63, 0x240, v181
	v_lshlrev_b32_e32 v64, 1, v182
	v_add_u32_e32 v63, v63, v64
	v_add_u32_e32 v63, v63, v62
	v_add_u32_e32 v63, 0xf000, v63
	v_lshrrev_b32_e32 v64, 3, v182
	v_lshl_add_u32 v64, v181, 2, v64
	v_and_b32_e32 v65, 7, v182
	v_mul_u32_u24_e32 v66, 0x90, v64
	v_lshl_add_u32 v66, v65, 4, v66
	v_add_u32_e32 v66, v66, v62
	v_add_u32_e32 v66, 0xf000, v66
	v_add_u32_e32 v67, v178, v64
	v_lshlrev_b32_e32 v67, 11, v67
	v_lshl_add_u32 v67, v65, 4, v67
	v_add_u32_e32 v84, 0x4000, v67
	v_add_u32_e32 v85, 0x8000, v67
	v_add_u32_e32 v86, 0xc000, v67
	s_waitcnt lgkmcnt(3)
	v_rcp_f32_e32 v42, v34
	v_rcp_f32_e32 v43, v35
	v_rcp_f32_e32 v44, v36
	v_rcp_f32_e32 v45, v37
	s_waitcnt lgkmcnt(2)
	v_rcp_f32_e32 v46, v38
	v_rcp_f32_e32 v47, v39
	v_rcp_f32_e32 v48, v40
	v_rcp_f32_e32 v49, v41
	s_waitcnt lgkmcnt(1)
	v_rcp_f32_e32 v50, v54
	v_rcp_f32_e32 v51, v55
	v_rcp_f32_e32 v52, v56
	v_rcp_f32_e32 v53, v57
	s_waitcnt lgkmcnt(0)
	v_rcp_f32_e32 v58, v58
	v_rcp_f32_e32 v59, v59
	v_rcp_f32_e32 v60, v60
	v_rcp_f32_e32 v61, v61
	v_mul_f32_e32 v68, v18, v42
	v_mul_f32_e32 v69, v2, v42
	v_cvt_pk_bf16_f32 v68, v68, v69
	ds_write_b16 v63, v68 offset:0
	ds_write_b16_d16_hi v63, v68 offset:64
	v_mul_f32_e32 v70, v19, v43
	v_mul_f32_e32 v71, v3, v43
	v_cvt_pk_bf16_f32 v70, v70, v71
	ds_write_b16 v63, v70 offset:144
	ds_write_b16_d16_hi v63, v70 offset:208
	v_mul_f32_e32 v72, v20, v44
	v_mul_f32_e32 v73, v4, v44
	v_cvt_pk_bf16_f32 v72, v72, v73
	ds_write_b16 v63, v72 offset:288
	ds_write_b16_d16_hi v63, v72 offset:352
	v_mul_f32_e32 v74, v21, v45
	v_mul_f32_e32 v75, v5, v45
	v_cvt_pk_bf16_f32 v74, v74, v75
	ds_write_b16 v63, v74 offset:432
	ds_write_b16_d16_hi v63, v74 offset:496
	v_mul_f32_e32 v68, v22, v46
	v_mul_f32_e32 v69, v6, v46
	v_cvt_pk_bf16_f32 v68, v68, v69
	ds_write_b16 v63, v68 offset:1152
	ds_write_b16_d16_hi v63, v68 offset:1216
	v_mul_f32_e32 v70, v23, v47
	v_mul_f32_e32 v71, v7, v47
	v_cvt_pk_bf16_f32 v70, v70, v71
	ds_write_b16 v63, v70 offset:1296
	ds_write_b16_d16_hi v63, v70 offset:1360
	v_mul_f32_e32 v72, v24, v48
	v_mul_f32_e32 v73, v8, v48
	v_cvt_pk_bf16_f32 v72, v72, v73
	ds_write_b16 v63, v72 offset:1440
	ds_write_b16_d16_hi v63, v72 offset:1504
	v_mul_f32_e32 v74, v25, v49
	v_mul_f32_e32 v75, v9, v49
	v_cvt_pk_bf16_f32 v74, v74, v75
	ds_write_b16 v63, v74 offset:1584
	ds_write_b16_d16_hi v63, v74 offset:1648
	v_mul_f32_e32 v68, v26, v50
	v_mul_f32_e32 v69, v10, v50
	v_cvt_pk_bf16_f32 v68, v68, v69
	ds_write_b16 v63, v68 offset:2304
	ds_write_b16_d16_hi v63, v68 offset:2368
	v_mul_f32_e32 v70, v27, v51
	v_mul_f32_e32 v71, v11, v51
	v_cvt_pk_bf16_f32 v70, v70, v71
	ds_write_b16 v63, v70 offset:2448
	ds_write_b16_d16_hi v63, v70 offset:2512
	v_mul_f32_e32 v72, v28, v52
	v_mul_f32_e32 v73, v12, v52
	v_cvt_pk_bf16_f32 v72, v72, v73
	ds_write_b16 v63, v72 offset:2592
	ds_write_b16_d16_hi v63, v72 offset:2656
	v_mul_f32_e32 v74, v29, v53
	v_mul_f32_e32 v75, v13, v53
	v_cvt_pk_bf16_f32 v74, v74, v75
	ds_write_b16 v63, v74 offset:2736
	ds_write_b16_d16_hi v63, v74 offset:2800
	v_mul_f32_e32 v68, v30, v58
	v_mul_f32_e32 v69, v14, v58
	v_cvt_pk_bf16_f32 v68, v68, v69
	ds_write_b16 v63, v68 offset:3456
	ds_write_b16_d16_hi v63, v68 offset:3520
	v_mul_f32_e32 v70, v31, v59
	v_mul_f32_e32 v71, v15, v59
	v_cvt_pk_bf16_f32 v70, v70, v71
	ds_write_b16 v63, v70 offset:3600
	ds_write_b16_d16_hi v63, v70 offset:3664
	v_mul_f32_e32 v72, v32, v60
	v_mul_f32_e32 v73, v16, v60
	v_cvt_pk_bf16_f32 v72, v72, v73
	ds_write_b16 v63, v72 offset:3744
	ds_write_b16_d16_hi v63, v72 offset:3808
	v_mul_f32_e32 v74, v33, v61
	v_mul_f32_e32 v75, v17, v61
	v_cvt_pk_bf16_f32 v74, v74, v75
	ds_write_b16 v63, v74 offset:3888
	ds_write_b16_d16_hi v63, v74 offset:3952
	s_waitcnt lgkmcnt(0)
	ds_read_b128 v[68:71], v66
	ds_read_b128 v[72:75], v66 offset:1152
	ds_read_b128 v[76:79], v66 offset:2304
	ds_read_b128 v[80:83], v66 offset:3456
	s_waitcnt lgkmcnt(3)
	global_store_dwordx4 v67, v[68:71], s[18:19]
	s_waitcnt lgkmcnt(2)
	global_store_dwordx4 v84, v[72:75], s[18:19]
	s_waitcnt lgkmcnt(1)
	global_store_dwordx4 v85, v[76:79], s[18:19]
	s_waitcnt lgkmcnt(0)
	global_store_dwordx4 v86, v[80:83], s[18:19]
	s_add_i32 s31, s31, s3
	s_cmp_lt_i32 s31, s21
	s_barrier
	s_cbranch_scc0 .LBB0_228

; #define SLOAD(i, k0) do { sr_[i].vs = BLD(rV, goff_kv, (k0) * 128); sr_[i].ks = BLD(rK, goff_kv, (k0) * 128); if (krt) sr_[i].kr = BLD(rR, goff_kr, (k0) * 64); } while (0)
; #define SWRITE(b, voff, i) do { *(bf16x8*)(V_lds + (voff) + vst0) = sr_[i].vs; *(bf16x8*)(K_lds + (b) * SHM_K + kst0) = sr_[i].ks; \
;     if (krt) *(bf16x8*)(K_lds + (b) * SHM_K + kst1) = sr_[i].kr; } while (0)
; #define SWAIT() do { asm volatile("s_waitcnt vmcnt(3)" ::: "memory"); } while (0)
; __device__ __forceinline__ void attn_unit(const bf16_t* __restrict__ Qb, const bf16_t* __restrict__ KNh, const bf16_t* __restrict__ KRb, const bf16_t* __restrict__ Vh,
;                                           bf16_t* __restrict__ Ob, int nkeys, char* lds, int tid_in) {
;     ...
;   SLOAD(SE, 0); asm volatile("s_waitcnt vmcnt(0)" ::: "memory"); SWRITE(0, 0, SE); __syncthreads();
;   phaseA<0, false>(pA0, pA1, pB0, pB1, pa0, pa1, pa2, pa3, qr, negm, kaddr, vf, vb0, l_reg);
;   alA = decide<true>(rowmax32(pA0, pA1), pA0, pA1, m_reg, negm);
;   SLOAD(SO, KVBLK); if (2 < NT) SLOAD(SE, 2 * KVBLK);
;   SWAIT(); SWRITE(1, SHM_V, SO); __syncthreads();
;   for (int j = 1; j + 1 < NT; j += 2) {
;     phaseA<1, true>(pB0, pB1, pA0, pA1, pa0, pa1, pa2, pa3, qr, negm, kaddr, vf, vb0 + vprev, l_reg);
.LBB0_244:
	s_or_b64 exec, exec, s[18:19]
	s_waitcnt vmcnt(3)
	s_waitcnt vmcnt(3)
	ds_write_b128 v187, v[34:37] offset:8192
	s_waitcnt vmcnt(2)
	ds_write_b128 v188, v[38:41] offset:37888
	v_add_u32_e32 v34, v45, v44
	s_and_saveexec_b64 s[18:19], vcc
	s_xor_b64 s[18:19], exec, s[18:19]
	v_add_u32_e32 v34, v45, v44
	s_andn2_saveexec_b64 s[18:19], s[18:19]
	v_add_u32_e32 v35, 0, v34
	ds_write_b128 v35, v[158:161] offset:38016
	s_or_b64 exec, exec, s[18:19]
	v_max_f32_e32 v36, v46, v46
	v_max_f32_e32 v0, v0, v0
	v_and_b32_e32 v35, 63, v42
	v_max_f32_e32 v0, v0, v36
	v_sub_f32_e32 v67, v3, v0
	v_lshlrev_b32_e32 v3, 4, v35
	v_sub_f32_e32 v68, v4, v0
	v_sub_f32_e32 v66, v2, v0
	v_lshlrev_b32_e32 v2, 3, v35
	v_and_b32_e32 v3, 0xc0, v3
	v_lshlrev_b32_e32 v4, 1, v35
	v_add_f32_e32 v189, 0, v0
	v_sub_f32_e32 v97, v33, v0
	v_sub_f32_e32 v96, v32, v0
	v_sub_f32_e32 v95, v31, v0
	v_sub_f32_e32 v94, v30, v0
	v_sub_f32_e32 v93, v29, v0
	v_sub_f32_e32 v92, v28, v0
	v_sub_f32_e32 v91, v27, v0
	v_sub_f32_e32 v90, v26, v0
	v_sub_f32_e32 v89, v25, v0
	v_sub_f32_e32 v88, v24, v0
	v_sub_f32_e32 v87, v23, v0
	v_sub_f32_e32 v86, v22, v0
	v_sub_f32_e32 v85, v21, v0
	v_sub_f32_e32 v84, v20, v0
	v_sub_f32_e32 v83, v19, v0
	v_sub_f32_e32 v82, v18, v0
	v_sub_f32_e32 v81, v17, v0
	v_sub_f32_e32 v80, v16, v0
	v_sub_f32_e32 v79, v15, v0
	v_sub_f32_e32 v78, v14, v0
	v_sub_f32_e32 v77, v13, v0
	v_sub_f32_e32 v76, v12, v0
	v_sub_f32_e32 v75, v11, v0
	v_sub_f32_e32 v74, v10, v0
	v_sub_f32_e32 v73, v9, v0
	v_sub_f32_e32 v72, v8, v0
	v_sub_f32_e32 v71, v7, v0
	v_sub_f32_e32 v70, v6, v0
	v_sub_f32_e32 v69, v5, v0
	v_and_b32_e32 v0, 0x3fffffc0, v42
	v_and_or_b32 v3, v2, 24, v3
	v_and_b32_e32 v4, 32, v4
	v_and_b32_e32 v2, 0x100, v2
	s_cmp_lg_u32 0, -1
	v_lshl_add_u32 v0, v0, 2, 0
	v_or3_b32 v2, v3, v4, v2
	s_cselect_b32 s19, 0, 0
	v_mov_b32_e32 v14, v1
	v_mov_b32_e32 v15, v1
	v_add_u32_e32 v192, s19, v2
	v_lshl_add_u32 v183, v182, 2, v0
	v_lshl_add_u32 v179, v181, 4, v0
	v_mov_b32_e32 v0, v1
	v_mov_b32_e32 v2, v1
	v_mov_b32_e32 v3, v1
	v_mov_b32_e32 v4, v1
	v_mov_b32_e32 v5, v1
	v_mov_b32_e32 v6, v1
	v_mov_b32_e32 v7, v1
	v_mov_b32_e32 v8, v1
	v_mov_b32_e32 v9, v1
	v_mov_b32_e32 v10, v1
	v_mov_b32_e32 v11, v1
	v_mov_b32_e32 v12, v1
	v_mov_b32_e32 v13, v1
	v_mov_b64_e32 v[32:33], v[14:15]
	v_xor_b32_e32 v50, 0x80000000, v189
	v_mov_b64_e32 v[30:31], v[12:13]
	v_mov_b64_e32 v[28:29], v[10:11]
	v_mov_b64_e32 v[26:27], v[8:9]
	v_mov_b64_e32 v[24:25], v[6:7]
	v_mov_b64_e32 v[22:23], v[4:5]
	v_mov_b64_e32 v[20:21], v[2:3]
	v_mov_b64_e32 v[18:19], v[0:1]
	v_mov_b64_e32 v[16:17], v[14:15]
	v_and_b32_e32 v178, 0xffffffe0, v43
	s_mov_b32 s39, 4
	s_mov_b32 s18, 0
	v_cmp_gt_u32_e64 s[40:41], 32, v35
	v_mov_b32_e32 v194, 0
	s_movk_i32 s53, 0x2000
	s_mov_b32 s52, 0x8000
	s_movk_i32 s68, 0x4000
	v_add_u32_e32 v193, 0, v34
	v_mov_b64_e32 v[14:15], v[12:13]
	v_mov_b64_e32 v[12:13], v[10:11]
	v_mov_b64_e32 v[10:11], v[8:9]
	v_mov_b64_e32 v[8:9], v[6:7]
	v_mov_b64_e32 v[6:7], v[4:5]
	v_mov_b64_e32 v[4:5], v[2:3]
	v_mov_b64_e32 v[2:3], v[0:1]
	s_movk_i32 s69, 0x4000
	v_mov_b32_e32 v51, v50
	v_mov_b32_e32 v52, v50
	v_mov_b32_e32 v53, v50
	v_mov_b32_e32 v54, v50
	v_mov_b32_e32 v55, v50
	v_mov_b32_e32 v56, v50
	v_mov_b32_e32 v57, v50
	v_mov_b32_e32 v58, v50
	v_mov_b32_e32 v59, v50
	v_mov_b32_e32 v60, v50
	v_mov_b32_e32 v61, v50
	v_mov_b32_e32 v62, v50
	v_mov_b32_e32 v63, v50
	v_mov_b32_e32 v64, v50
	v_mov_b32_e32 v65, v50
	s_waitcnt lgkmcnt(0)
	s_mov_b32 s76, s53
	s_mov_b32 s53, s18
	v_add_u32_e32 v0, s53, v192
	s_cmp_lg_u64 s[42:43], 0
	s_cbranch_scc0 .Lmy_y249
.LBB0_249:
	s_barrier
	ds_read_b128 v[34:37], v184 offset:0x3400
	ds_read_b128 v[38:41], v184 offset:0x4e00
	ds_read_b128 v[42:45], v184 offset:0x3420
	ds_read_b128 v[46:49], v184 offset:0x4e20
	ds_read_b128 v[170:173], v184 offset:0x3440
	ds_read_b128 v[174:177], v184 offset:0x4e40
	ds_read_b128 v[204:207], v184 offset:0x3460
	ds_read_b128 v[208:211], v184 offset:0x4e60
	v_exp_f32_e32 v82, v82
	v_exp_f32_e32 v195, v83
	v_exp_f32_e32 v84, v84
	v_exp_f32_e32 v196, v85
	v_exp_f32_e32 v83, v86
	v_exp_f32_e32 v85, v87
	v_exp_f32_e32 v86, v88
	v_exp_f32_e32 v87, v89
	s_waitcnt lgkmcnt(7)
	v_mfma_f32_32x32x16_bf16 v[114:129], v[34:37], v[150:153], v[50:65]
	v_exp_f32_e32 v88, v90
	v_exp_f32_e32 v89, v91
	v_exp_f32_e32 v90, v92
	v_exp_f32_e32 v91, v93
	s_waitcnt lgkmcnt(6)
	v_mfma_f32_32x32x16_bf16 v[98:113], v[38:41], v[150:153], v[50:65]
	v_exp_f32_e32 v92, v94
	v_exp_f32_e32 v93, v95
	v_exp_f32_e32 v94, v96
	v_exp_f32_e32 v95, v97
	s_waitcnt lgkmcnt(5)
	v_mfma_f32_32x32x16_bf16 v[114:129], v[42:45], v[146:149], v[114:129]
	v_cvt_pk_bf16_f32 v34, v82, v195
	v_cvt_pk_bf16_f32 v35, v84, v196
	v_cvt_pk_bf16_f32 v36, v83, v85
	v_cvt_pk_bf16_f32 v37, v86, v87
	s_waitcnt lgkmcnt(4)
	v_mfma_f32_32x32x16_bf16 v[98:113], v[46:49], v[146:149], v[98:113]
	v_exp_f32_e32 v96, v66
	v_exp_f32_e32 v97, v67
	v_exp_f32_e32 v197, v68
	v_exp_f32_e32 v198, v69
	ds_read_b128 v[38:41], v184 offset:0x3480
	ds_read_b128 v[66:69], v184 offset:0x4e80
	ds_read_b128 v[212:215], v184 offset:0x34a0
	ds_read_b128 v[216:219], v184 offset:0x4ea0
	s_waitcnt lgkmcnt(4)
	v_mfma_f32_32x32x16_bf16 v[114:129], v[170:173], v[142:145], v[114:129]
	v_exp_f32_e32 v199, v70
	v_exp_f32_e32 v200, v71
	v_exp_f32_e32 v201, v72
	v_exp_f32_e32 v202, v73
	v_mfma_f32_32x32x16_bf16 v[98:113], v[174:177], v[142:145], v[98:113]
	v_cvt_pk_bf16_f32 v42, v88, v89
	v_cvt_pk_bf16_f32 v43, v90, v91
	v_cvt_pk_bf16_f32 v44, v92, v93
	v_cvt_pk_bf16_f32 v45, v94, v95
	v_mfma_f32_32x32x16_bf16 v[114:129], v[204:207], v[138:141], v[114:129]
	v_exp_f32_e32 v203, v74
	v_exp_f32_e32 v204, v75
	v_exp_f32_e32 v205, v76
	v_exp_f32_e32 v206, v77
	v_mfma_f32_32x32x16_bf16 v[98:113], v[208:211], v[138:141], v[98:113]
	v_exp_f32_e32 v207, v78
	v_exp_f32_e32 v208, v79
	v_exp_f32_e32 v209, v80
	v_exp_f32_e32 v210, v81
	s_waitcnt lgkmcnt(0)
; #define SBAR() __builtin_amdgcn_sched_barrier(0)
; template <int KB, bool HASY>
; __device__ __forceinline__ void phaseA(f32x16& X0, f32x16& X1, f32x16& Y0, f32x16& Y1, bf16x8& pa0, bf16x8& pa1, bf16x8& pa2, bf16x8& pa3,
;                                        const bf16x8* qr, const f32x16& negm, int kaddr, VFr& vf, int vb, float& l_reg) {
;     ...
;   X1 = MF(k11, qr[5], X1); if (HASY) vfr_issue<0>(vf, vb);
;   l_reg += ls;
;   SBAR();
; }
; template <bool HASX>
; __device__ __forceinline__ float phaseB(f32x16* o, bf16x8 pa0, bf16x8 pa1, bf16x8 pa2, bf16x8 pa3, VFr& f, int vb, const f32x16& X0, const f32x16& X1) {
;   SBAR(); VWAIT(f); VFr g; vfr_issue<2>(g, vb); SBAR();
;   float a = 0.f, b = 0.f;
;   o[0] = MF(pa0, PKV(f.a0, f.b0), o[0]); SBAR(); o[1] = MF(pa0, PKV(f.c0, f.d0), o[1]);
;   if (HASX) { a = MX3(X0[0], X0[1], X1[0]); b = MX3(X0[2], X0[3], X1[1]); a = MX3(a, X1[2], X1[3]); b = MX3(b, X0[4], X0[5]); } SBAR();
;   o[0] = MF(pa1, PKV(f.a1, f.b1), o[0]); if (HASX) { a = MX3(a, X0[6], X0[7]); b = MX3(b, X1[4], X1[5]); } SBAR();
;   o[1] = MF(pa1, PKV(f.c1, f.d1), o[1]); if (HASX) { a = MX3(a, X1[6], X1[7]); b = MX3(b, X0[8], X0[9]); a = MX3(a, X0[10], X0[11]); } SBAR();
;   VWAIT(g); SBAR();
;   o[0] = MF(pa2, PKV(g.a0, g.b0), o[0]); if (HASX) { b = MX3(b, X1[8], X1[9]); a = MX3(a, X1[10], X1[11]); } SBAR();
;   o[1] = MF(pa2, PKV(g.c0, g.d0), o[1]); if (HASX) { b = MX3(b, X0[12], X0[13]); a = MX3(a, X0[14], X0[15]); } SBAR();
;   o[0] = MF(pa3, PKV(g.a1, g.b1), o[0]); if (HASX) { b = MX3(b, X1[12], X1[13]); a = MX3(a, X1[14], X1[15]); } SBAR();
;   o[1] = MF(pa3, PKV(g.c1, g.d1), o[1]); SBAR();
;   float pmax = __builtin_fmaxf(a, b);
;   if (HASX) { auto rr = __builtin_amdgcn_permlane32_swap(__float_as_uint(pmax), __float_as_uint(pmax), false, false); pmax = __builtin_fmaxf(__uint_as_float(rr[0]), __uint_as_float(rr[1])); }
;   return pmax;
; }
; __device__ __forceinline__ void attn_unit(const bf16_t* __restrict__ Qb, const bf16_t* __restrict__ KNh, const bf16_t* __restrict__ KRb, const bf16_t* __restrict__ Vh,
;                                           bf16_t* __restrict__ Ob, int nkeys, char* lds, int tid_in) {
;     ...
;     SLOAD(SO, (j + 2) * KVBLK); SBAR();
;     alB = decide<false>(phaseB<true>(o, pa0, pa1, pa2, pa3, vf, vb0 + vprev, pB0, pB1), pB0, pB1, m_reg, negm);
;     SWAIT(); SWRITE(0, vnext, SE);
	s_nop 0
	v_mfma_f32_32x32x16_bf16 v[114:129], v[38:41], v[134:137], v[114:129]
	v_cvt_pk_bf16_f32 v46, v96, v97
	v_cvt_pk_bf16_f32 v47, v197, v198
	v_cvt_pk_bf16_f32 v48, v199, v200
	v_cvt_pk_bf16_f32 v49, v201, v202
	v_mfma_f32_32x32x16_bf16 v[98:113], v[66:69], v[134:137], v[98:113]
	v_mfma_f32_32x32x16_bf16 v[114:129], v[212:215], v[130:133], v[114:129]
	v_cvt_pk_bf16_f32 v38, v203, v204
	v_cvt_pk_bf16_f32 v39, v205, v206
	v_cvt_pk_bf16_f32 v40, v207, v208
	v_cvt_pk_bf16_f32 v41, v209, v210
	ds_read_b64_tr_b16 v[78:79], v0 offset:0
	ds_read_b64_tr_b16 v[80:81], v0 offset:0x400
	ds_read_b64_tr_b16 v[74:75], v0 offset:0x200
	v_mfma_f32_32x32x16_bf16 v[98:113], v[216:219], v[130:133], v[98:113]
	ds_read_b64_tr_b16 v[76:77], v0 offset:0x600
	ds_read_b64_tr_b16 v[70:71], v0 offset:0x800
	ds_read_b64_tr_b16 v[72:73], v0 offset:0xc00
	ds_read_b64_tr_b16 v[66:67], v0 offset:0xa00
	ds_read_b64_tr_b16 v[68:69], v0 offset:0xe00
	s_add_i32 s18, s52, 0xffffe000
	buffer_load_dwordx4 v[170:173], v185, s[64:67], s18 offen
	buffer_load_dwordx4 v[174:177], v185, s[44:47], s18 offen
	s_add_i32 s28, s68, 0xfffff000
	buffer_load_dwordx4 v[158:161], v186, s[60:63], s28 offen
	s_waitcnt lgkmcnt(0)
	ds_read_b64_tr_b16 v[212:213], v0 offset:0x1000
	ds_read_b64_tr_b16 v[214:215], v0 offset:0x1400
	ds_read_b64_tr_b16 v[216:217], v0 offset:0x1200
	ds_read_b64_tr_b16 v[218:219], v0 offset:0x1600
	ds_read_b64_tr_b16 v[220:221], v0 offset:0x1800
	ds_read_b64_tr_b16 v[222:223], v0 offset:0x1c00
	ds_read_b64_tr_b16 v[228:229], v0 offset:0x1a00
	ds_read_b64_tr_b16 v[230:231], v0 offset:0x1e00
	v_mfma_f32_32x32x16_bf16 v[18:33], v[34:37], v[78:81], v[18:33]
	v_add_f32_e32 v238, v82, v195
	v_add_f32_e32 v239, v84, v196
	v_add_f32_e32 v240, v83, v85
	v_add_f32_e32 v241, v86, v87
	v_add_f32_e32 v238, v238, v239
	v_add_f32_e32 v240, v240, v241
	v_mfma_f32_32x32x16_bf16 v[2:17], v[34:37], v[74:77], v[2:17]
	v_max_f32_e32 v34, v114, v115
	v_max3_f32 v35, v116, v117, v99
	v_max3_f32 v34, v34, v98, v100
	v_max3_f32 v35, v35, v118, v119
	v_mfma_f32_32x32x16_bf16 v[18:33], v[42:45], v[70:73], v[18:33]
	v_max3_f32 v34, v34, v101, v120
	v_max3_f32 v35, v35, v102, v103
	v_add_f32_e32 v238, v240, v238
	v_add_f32_e32 v239, v88, v89
	v_add_f32_e32 v241, v90, v91
	v_mfma_f32_32x32x16_bf16 v[2:17], v[42:45], v[66:69], v[2:17]
	v_max3_f32 v34, v34, v121, v104
	v_max3_f32 v34, v34, v105, v124
	v_max3_f32 v35, v35, v122, v123
	v_add_f32_e32 v239, v239, v241
	v_add_f32_e32 v240, v92, v93
	v_add_f32_e32 v241, v94, v95
	s_waitcnt lgkmcnt(0)
	v_mfma_f32_32x32x16_bf16 v[18:33], v[46:49], v[212:215], v[18:33]
	v_max3_f32 v34, v34, v125, v108
	v_max3_f32 v35, v35, v106, v107
	v_add_f32_e32 v238, v239, v238
	v_add_f32_e32 v240, v240, v241
	s_waitcnt vmcnt(3)
	v_add_u32_e32 v67, s69, v187
	ds_write_b128 v67, v[162:165]
	v_mfma_f32_32x32x16_bf16 v[2:17], v[46:49], v[216:219], v[2:17]
	v_max3_f32 v34, v34, v109, v128
	v_max3_f32 v35, v35, v126, v127
	v_add_f32_e32 v238, v240, v238
	v_add_f32_e32 v239, v96, v97
	v_add_f32_e32 v241, v197, v198
	s_waitcnt vmcnt(2)
	ds_write_b128 v188, v[166:169] offset:24576
	v_mfma_f32_32x32x16_bf16 v[18:33], v[38:41], v[220:223], v[18:33]
	v_max3_f32 v34, v34, v129, v112
	v_max3_f32 v35, v35, v110, v111
	v_add_f32_e32 v239, v239, v241
	v_add_f32_e32 v240, v199, v200
	v_add_f32_e32 v241, v201, v202
	ds_write_b128 v193, v[154:157] offset:24704
	v_add_f32_e32 v238, v239, v238
	v_add_f32_e32 v240, v240, v241
	v_mfma_f32_32x32x16_bf16 v[2:17], v[38:41], v[228:231], v[2:17]
	v_max3_f32 v34, v34, v113, v35
	v_cmp_lt_f32_e32 vcc, s35, v34
	v_add_f32_e32 v238, v240, v238
	v_add_f32_e32 v239, v203, v204
	v_add_f32_e32 v241, v205, v206
	v_add_f32_e32 v239, v239, v241
	v_add_f32_e32 v240, v207, v208
	v_add_f32_e32 v241, v209, v210
	v_add_f32_e32 v238, v239, v238
	v_add_f32_e32 v240, v240, v241
	v_add_f32_e32 v238, v240, v238
	v_add_f32_e32 v194, v194, v238
	s_cbranch_vccnz .LBB0_272
; template <int KB, bool HASY>
; __device__ __forceinline__ void phaseA(f32x16& X0, f32x16& X1, f32x16& Y0, f32x16& Y1, bf16x8& pa0, bf16x8& pa1, bf16x8& pa2, bf16x8& pa3,
;                                        const bf16x8* qr, const f32x16& negm, int kaddr, VFr& vf, int vb, float& l_reg) {
;   SBAR();
;   float ls = 0.f;
;   bf16x8 k0 = rd128<KOFF(KB, 0, 0)>(kaddr), k1 = rd128<KOFF(KB, 1, 0)>(kaddr), k2 = rd128<KOFF(KB, 0, 1)>(kaddr), k3 = rd128<KOFF(KB, 1, 1)>(kaddr);
;   if (HASY) { EXP4(Y0, 0); EXP4(Y0, 4); }
;   SBAR(); WAIT4(k0, k1, k2, k3);
;   bf16x8 k4 = rd128<KOFF(KB, 0, 2)>(kaddr), k5 = rd128<KOFF(KB, 1, 2)>(kaddr), k6 = rd128<KOFF(KB, 0, 3)>(kaddr), k7 = rd128<KOFF(KB, 1, 3)>(kaddr);
;   SBAR();
;   X0 = MF(k0, qr[0], negm); if (HASY) { EXP4(Y0, 8); SUM4(Y0, 0); } SBAR();
;   X1 = MF(k1, qr[0], negm); if (HASY) { EXP4(Y0, 12); SUM4(Y0, 4); } SBAR();
;   X0 = MF(k2, qr[1], X0); if (HASY) { PACK8(Y0, 0, pa0); } SBAR();
;   X1 = MF(k3, qr[1], X1); if (HASY) { EXP4(Y1, 0); SUM4(Y0, 8); } SBAR();
;   WAIT4(k4, k5, k6, k7);
;   bf16x8 k8 = rd128<KOFF(KB, 0, 4)>(kaddr), k9 = rd128<KOFF(KB, 1, 4)>(kaddr), k10 = rd128<KOFF(KB, 0, 5)>(kaddr), k11 = rd128<KOFF(KB, 1, 5)>(kaddr);
;   SBAR();
;   X0 = MF(k4, qr[2], X0); if (HASY) { EXP4(Y1, 4); SUM4(Y0, 12); } SBAR();
;   X1 = MF(k5, qr[2], X1); if (HASY) { PACK8(Y0, 8, pa1); } SBAR();
;   X0 = MF(k6, qr[3], X0); if (HASY) { EXP4(Y1, 8); SUM4(Y1, 0); } SBAR();
;   X1 = MF(k7, qr[3], X1); if (HASY) { EXP4(Y1, 12); SUM4(Y1, 4); } SBAR();
;   WAIT4(k8, k9, k10, k11);
;   SBAR();
;   X0 = MF(k8, qr[4], X0); if (HASY) { PACK8(Y1, 0, pa2); } SBAR();
;   X1 = MF(k9, qr[4], X1); if (HASY) { SUM4(Y1, 8); SUM4(Y1, 12); } SBAR();
;   X0 = MF(k10, qr[5], X0); if (HASY) { PACK8(Y1, 8, pa3); } SBAR();
;   X1 = MF(k11, qr[5], X1); if (HASY) vfr_issue<0>(vf, vb);
;   l_reg += ls;
;   SBAR();
; }
; template <bool HASX>
; __device__ __forceinline__ float phaseB(f32x16* o, bf16x8 pa0, bf16x8 pa1, bf16x8 pa2, bf16x8 pa3, VFr& f, int vb, const f32x16& X0, const f32x16& X1) {
;   SBAR(); VWAIT(f); VFr g; vfr_issue<2>(g, vb); SBAR();
;   float a = 0.f, b = 0.f;
;   o[0] = MF(pa0, PKV(f.a0, f.b0), o[0]); SBAR(); o[1] = MF(pa0, PKV(f.c0, f.d0), o[1]);
;   if (HASX) { a = MX3(X0[0], X0[1], X1[0]); b = MX3(X0[2], X0[3], X1[1]); a = MX3(a, X1[2], X1[3]); b = MX3(b, X0[4], X0[5]); } SBAR();
.LBB0_259:
	v_add_u32_e32 v237, s76, v192
	s_waitcnt lgkmcnt(0)
	s_barrier
	ds_read_b128 v[66:69], v184 offset:0
	ds_read_b128 v[212:215], v184 offset:0x1a00
	ds_read_b128 v[216:219], v184 offset:32
	v_exp_f32_e32 v195, v114
	v_exp_f32_e32 v197, v115
	v_exp_f32_e32 v198, v116
	v_exp_f32_e32 v201, v117
	v_exp_f32_e32 v196, v118
	v_exp_f32_e32 v199, v119
	v_exp_f32_e32 v200, v120
	v_exp_f32_e32 v202, v121
	ds_read_b128 v[118:121], v184 offset:0x1a20
	ds_read_b128 v[220:223], v184 offset:64
	ds_read_b128 v[228:231], v184 offset:0x1a40
	ds_read_b128 v[238:241], v184 offset:0x60
	ds_read_b128 v[242:245], v184 offset:0x1a60
	s_waitcnt lgkmcnt(7)
	v_mfma_f32_32x32x16_bf16 v[82:97], v[66:69], v[150:153], v[50:65]
	v_exp_f32_e32 v203, v122
	v_exp_f32_e32 v204, v123
	v_exp_f32_e32 v205, v124
	v_exp_f32_e32 v206, v125
	s_waitcnt lgkmcnt(6)
	v_mfma_f32_32x32x16_bf16 v[66:81], v[212:215], v[150:153], v[50:65]
	v_exp_f32_e32 v207, v126
	v_exp_f32_e32 v208, v127
	v_exp_f32_e32 v209, v128
	v_exp_f32_e32 v210, v129
	s_waitcnt lgkmcnt(5)
	v_mfma_f32_32x32x16_bf16 v[82:97], v[216:219], v[146:149], v[82:97]
	v_cvt_pk_bf16_f32 v114, v195, v197
	v_cvt_pk_bf16_f32 v115, v198, v201
	v_cvt_pk_bf16_f32 v116, v196, v199
	v_cvt_pk_bf16_f32 v117, v200, v202
	s_waitcnt lgkmcnt(4)
	v_mfma_f32_32x32x16_bf16 v[66:81], v[118:121], v[146:149], v[66:81]
	v_exp_f32_e32 v211, v98
	v_exp_f32_e32 v212, v99
	v_exp_f32_e32 v213, v100
	v_exp_f32_e32 v214, v101
	ds_read_b128 v[98:101], v184 offset:0x80
	ds_read_b128 v[118:121], v184 offset:0x1a80
	ds_read_b128 v[122:125], v184 offset:0xa0
	ds_read_b128 v[246:249], v184 offset:0x1aa0
	s_waitcnt lgkmcnt(4)
	v_mfma_f32_32x32x16_bf16 v[82:97], v[220:223], v[142:145], v[82:97]
	v_exp_f32_e32 v215, v102
	v_exp_f32_e32 v216, v103
	v_exp_f32_e32 v217, v104
	v_exp_f32_e32 v218, v105
	v_mfma_f32_32x32x16_bf16 v[66:81], v[228:231], v[142:145], v[66:81]
	v_cvt_pk_bf16_f32 v102, v203, v204
	v_cvt_pk_bf16_f32 v103, v205, v206
	v_cvt_pk_bf16_f32 v104, v207, v208
	v_cvt_pk_bf16_f32 v105, v209, v210
	v_mfma_f32_32x32x16_bf16 v[82:97], v[238:241], v[138:141], v[82:97]
	v_exp_f32_e32 v219, v106
	v_exp_f32_e32 v220, v107
	v_exp_f32_e32 v221, v108
	v_exp_f32_e32 v222, v109
	v_mfma_f32_32x32x16_bf16 v[66:81], v[242:245], v[138:141], v[66:81]
	v_exp_f32_e32 v223, v110
	v_exp_f32_e32 v234, v111
	v_exp_f32_e32 v235, v112
	v_exp_f32_e32 v236, v113
	s_waitcnt lgkmcnt(0)
	s_nop 0
	v_mfma_f32_32x32x16_bf16 v[82:97], v[98:101], v[134:137], v[82:97]
	v_cvt_pk_bf16_f32 v106, v211, v212
	v_cvt_pk_bf16_f32 v107, v213, v214
	v_cvt_pk_bf16_f32 v108, v215, v216
	v_cvt_pk_bf16_f32 v109, v217, v218
	v_mfma_f32_32x32x16_bf16 v[66:81], v[118:121], v[134:137], v[66:81]
	v_mfma_f32_32x32x16_bf16 v[82:97], v[122:125], v[130:133], v[82:97]
	v_cvt_pk_bf16_f32 v98, v219, v220
	v_cvt_pk_bf16_f32 v99, v221, v222
	v_cvt_pk_bf16_f32 v100, v223, v234
	v_cvt_pk_bf16_f32 v101, v235, v236
	ds_read_b64_tr_b16 v[126:127], v237 offset:0
	ds_read_b64_tr_b16 v[128:129], v237 offset:0x400
	ds_read_b64_tr_b16 v[122:123], v237 offset:0x200
	v_mfma_f32_32x32x16_bf16 v[66:81], v[246:249], v[130:133], v[66:81]
	ds_read_b64_tr_b16 v[124:125], v237 offset:0x600
	ds_read_b64_tr_b16 v[118:119], v237 offset:0x800
	ds_read_b64_tr_b16 v[120:121], v237 offset:0xc00
	ds_read_b64_tr_b16 v[110:111], v237 offset:0xa00
	ds_read_b64_tr_b16 v[112:113], v237 offset:0xe00
	s_cmp_ge_u32 s39, s38
	s_cselect_b64 s[18:19], -1, 0
	s_and_b64 vcc, exec, s[18:19]
	s_cbranch_vccnz .LBB0_263
	buffer_load_dwordx4 v[162:165], v185, s[64:67], s52 offen
	buffer_load_dwordx4 v[166:169], v185, s[44:47], s52 offen
	buffer_load_dwordx4 v[154:157], v186, s[60:63], s68 offen
.LBB0_263:
	s_waitcnt lgkmcnt(0)
	ds_read_b64_tr_b16 v[228:229], v237 offset:0x1000
	ds_read_b64_tr_b16 v[230:231], v237 offset:0x1400
	ds_read_b64_tr_b16 v[238:239], v237 offset:0x1200
	ds_read_b64_tr_b16 v[240:241], v237 offset:0x1600
	ds_read_b64_tr_b16 v[242:243], v237 offset:0x1800
	ds_read_b64_tr_b16 v[244:245], v237 offset:0x1c00
	ds_read_b64_tr_b16 v[246:247], v237 offset:0x1a00
	ds_read_b64_tr_b16 v[248:249], v237 offset:0x1e00
	v_mfma_f32_32x32x16_bf16 v[18:33], v[114:117], v[126:129], v[18:33]
	v_add_f32_e32 v34, v195, v197
	v_add_f32_e32 v35, v198, v201
	v_add_f32_e32 v36, v196, v199
	v_add_f32_e32 v37, v200, v202
	v_add_f32_e32 v34, v34, v35
	v_add_f32_e32 v36, v36, v37
	v_mfma_f32_32x32x16_bf16 v[2:17], v[114:117], v[122:125], v[2:17]
	v_max_f32_e32 v114, v82, v83
	v_max3_f32 v115, v84, v85, v67
	v_max3_f32 v114, v114, v66, v68
	v_max3_f32 v115, v115, v86, v87
	v_mfma_f32_32x32x16_bf16 v[18:33], v[102:105], v[118:121], v[18:33]
	v_max3_f32 v114, v114, v69, v88
	v_max3_f32 v115, v115, v70, v71
	v_add_f32_e32 v34, v36, v34
	v_add_f32_e32 v35, v203, v204
	v_add_f32_e32 v37, v205, v206
	v_mfma_f32_32x32x16_bf16 v[2:17], v[102:105], v[110:113], v[2:17]
	v_max3_f32 v102, v114, v89, v72
	v_max3_f32 v103, v115, v90, v91
	v_max3_f32 v102, v102, v73, v92
	v_add_f32_e32 v35, v35, v37
	v_add_f32_e32 v36, v207, v208
	v_add_f32_e32 v37, v209, v210
	s_waitcnt lgkmcnt(0)
	v_mfma_f32_32x32x16_bf16 v[18:33], v[106:109], v[228:231], v[18:33]
	v_max3_f32 v103, v103, v74, v75
	v_max3_f32 v102, v102, v93, v76
	v_add_f32_e32 v34, v35, v34
	v_add_f32_e32 v36, v36, v37
	s_cmp_ge_u32 s39, s38
	s_cbranch_scc0 .Lmy_h1w
	s_waitcnt vmcnt(0)

; #define SBAR() __builtin_amdgcn_sched_barrier(0)
; #define SLOAD(i, k0) do { sr_[i].vs = BLD(rV, goff_kv, (k0) * 128); sr_[i].ks = BLD(rK, goff_kv, (k0) * 128); if (krt) sr_[i].kr = BLD(rR, goff_kr, (k0) * 64); } while (0)
; #define SWRITE(b, voff, i) do { *(bf16x8*)(V_lds + (voff) + vst0) = sr_[i].vs; *(bf16x8*)(K_lds + (b) * SHM_K + kst0) = sr_[i].ks; \
;     if (krt) *(bf16x8*)(K_lds + (b) * SHM_K + kst1) = sr_[i].kr; } while (0)
; #define SWAIT() do { asm volatile("s_waitcnt vmcnt(3)" ::: "memory"); } while (0)
; #define RESC(a) do { if (__any((a) < 1.f)) { if (hi == 0) al_l[r32] = (a); asm volatile("s_waitcnt lgkmcnt(0)" ::: "memory"); l_reg *= (a); \
;     _Pragma("unroll") for (int d = 0; d < 2; ++d) _Pragma("unroll") for (int r = 0; r < 16; ++r) o[d][r] *= al_l[crow(r, hi)]; } } while (0)
; #define ROT() do { const int t_ = vprev; vprev = vcur; vcur = vnext; vnext = t_; } while (0)
; __device__ __forceinline__ void attn_unit(const bf16_t* __restrict__ Qb, const bf16_t* __restrict__ KNh, const bf16_t* __restrict__ KRb, const bf16_t* __restrict__ Vh,
;                                           bf16_t* __restrict__ Ob, int nkeys, char* lds, int tid_in) {
;     ...
;   for (int j = 1; j + 1 < NT; j += 2) {
;     phaseA<1, true>(pB0, pB1, pA0, pA1, pa0, pa1, pa2, pa3, qr, negm, kaddr, vf, vb0 + vprev, l_reg);
;     SLOAD(SO, (j + 2) * KVBLK); SBAR();
;     alB = decide<false>(phaseB<true>(o, pa0, pa1, pa2, pa3, vf, vb0 + vprev, pB0, pB1), pB0, pB1, m_reg, negm);
;     SWAIT(); SWRITE(0, vnext, SE);
;     RESC(alB); __syncthreads(); ROT();
;     phaseA<0, true>(pA0, pA1, pB0, pB1, pa0, pa1, pa2, pa3, qr, negm, kaddr, vf, vb0 + vprev, l_reg);
;     if (j + 3 < NT) SLOAD(SE, (j + 3) * KVBLK); SBAR();
;     alA = decide<false>(phaseB<true>(o, pa0, pa1, pa2, pa3, vf, vb0 + vprev, pA0, pA1), pA0, pA1, m_reg, negm);
;     SWAIT(); SWRITE(1, vnext, SO);
;     RESC(alA); __syncthreads(); ROT();
;   }
.LBB0_270:
	s_addk_i32 s52, 0x4000
	s_addk_i32 s68, 0x2000
	s_add_i32 s39, s39, 2
	s_and_b64 vcc, exec, s[18:19]
	s_waitcnt lgkmcnt(0)
	s_cbranch_vccnz .Lmy_xexit
	s_mov_b32 s18, s69
	s_mov_b32 s69, s76
	s_mov_b32 s76, s53
	s_mov_b32 s53, s18
	v_add_u32_e32 v0, s53, v192
	s_branch .LBB0_249
.Lmy_xexit:
	s_barrier
	s_branch .LBB0_274

; template <int KB, bool HASY>
; __device__ __forceinline__ void phaseA(f32x16& X0, f32x16& X1, f32x16& Y0, f32x16& Y1, bf16x8& pa0, bf16x8& pa1, bf16x8& pa2, bf16x8& pa3,
;                                        const bf16x8* qr, const f32x16& negm, int kaddr, VFr& vf, int vb, float& l_reg) {
;   SBAR();
;   float ls = 0.f;
;   bf16x8 k0 = rd128<KOFF(KB, 0, 0)>(kaddr), k1 = rd128<KOFF(KB, 1, 0)>(kaddr), k2 = rd128<KOFF(KB, 0, 1)>(kaddr), k3 = rd128<KOFF(KB, 1, 1)>(kaddr);
;   if (HASY) { EXP4(Y0, 0); EXP4(Y0, 4); }
;   SBAR(); WAIT4(k0, k1, k2, k3);
;   bf16x8 k4 = rd128<KOFF(KB, 0, 2)>(kaddr), k5 = rd128<KOFF(KB, 1, 2)>(kaddr), k6 = rd128<KOFF(KB, 0, 3)>(kaddr), k7 = rd128<KOFF(KB, 1, 3)>(kaddr);
;   SBAR();
;   X0 = MF(k0, qr[0], negm); if (HASY) { EXP4(Y0, 8); SUM4(Y0, 0); } SBAR();
;   X1 = MF(k1, qr[0], negm); if (HASY) { EXP4(Y0, 12); SUM4(Y0, 4); } SBAR();
;   X0 = MF(k2, qr[1], X0); if (HASY) { PACK8(Y0, 0, pa0); } SBAR();
;   X1 = MF(k3, qr[1], X1); if (HASY) { EXP4(Y1, 0); SUM4(Y0, 8); } SBAR();
;   WAIT4(k4, k5, k6, k7);
;   bf16x8 k8 = rd128<KOFF(KB, 0, 4)>(kaddr), k9 = rd128<KOFF(KB, 1, 4)>(kaddr), k10 = rd128<KOFF(KB, 0, 5)>(kaddr), k11 = rd128<KOFF(KB, 1, 5)>(kaddr);
;   SBAR();
;   X0 = MF(k4, qr[2], X0); if (HASY) { EXP4(Y1, 4); SUM4(Y0, 12); } SBAR();
;   X1 = MF(k5, qr[2], X1); if (HASY) { PACK8(Y0, 8, pa1); } SBAR();
;   X0 = MF(k6, qr[3], X0); if (HASY) { EXP4(Y1, 8); SUM4(Y1, 0); } SBAR();
;   X1 = MF(k7, qr[3], X1); if (HASY) { EXP4(Y1, 12); SUM4(Y1, 4); } SBAR();
;   WAIT4(k8, k9, k10, k11);
;   SBAR();
;   X0 = MF(k8, qr[4], X0); if (HASY) { PACK8(Y1, 0, pa2); } SBAR();
;   X1 = MF(k9, qr[4], X1); if (HASY) { SUM4(Y1, 8); SUM4(Y1, 12); } SBAR();
;   X0 = MF(k10, qr[5], X0); if (HASY) { PACK8(Y1, 8, pa3); } SBAR();
;   X1 = MF(k11, qr[5], X1); if (HASY) vfr_issue<0>(vf, vb);
;   l_reg += ls;
;   SBAR();
; }
; template <bool HASX>
; __device__ __forceinline__ float phaseB(f32x16* o, bf16x8 pa0, bf16x8 pa1, bf16x8 pa2, bf16x8 pa3, VFr& f, int vb, const f32x16& X0, const f32x16& X1) {
;   SBAR(); VWAIT(f); VFr g; vfr_issue<2>(g, vb); SBAR();
;   float a = 0.f, b = 0.f;
;   o[0] = MF(pa0, PKV(f.a0, f.b0), o[0]); SBAR(); o[1] = MF(pa0, PKV(f.c0, f.d0), o[1]);
;   if (HASX) { a = MX3(X0[0], X0[1], X1[0]); b = MX3(X0[2], X0[3], X1[1]); a = MX3(a, X1[2], X1[3]); b = MX3(b, X0[4], X0[5]); } SBAR();
.Lmy_y249:
	s_barrier
	ds_read_b128 v[34:37], v184 offset:0x3400
	ds_read_b128 v[38:41], v184 offset:0x4e00
	ds_read_b128 v[42:45], v184 offset:0x3420
	ds_read_b128 v[46:49], v184 offset:0x4e20
	ds_read_b128 v[170:173], v184 offset:0x3440
	ds_read_b128 v[174:177], v184 offset:0x4e40
	ds_read_b128 v[204:207], v184 offset:0x3460
	ds_read_b128 v[208:211], v184 offset:0x4e60
	v_exp_f32_e32 v82, v82
	v_exp_f32_e32 v195, v83
	v_exp_f32_e32 v84, v84
	v_exp_f32_e32 v196, v85
	v_exp_f32_e32 v83, v86
	v_exp_f32_e32 v85, v87
	v_exp_f32_e32 v86, v88
	v_exp_f32_e32 v87, v89
	s_waitcnt lgkmcnt(7)
	v_mfma_f32_32x32x16_bf16 v[114:129], v[34:37], v[150:153], v[50:65]
	v_exp_f32_e32 v88, v90
	v_exp_f32_e32 v89, v91
	v_exp_f32_e32 v90, v92
	v_exp_f32_e32 v91, v93
	s_waitcnt lgkmcnt(6)
	v_mfma_f32_32x32x16_bf16 v[98:113], v[38:41], v[150:153], v[50:65]
	v_exp_f32_e32 v92, v94
	v_exp_f32_e32 v93, v95
	v_exp_f32_e32 v94, v96
	v_exp_f32_e32 v95, v97
	s_waitcnt lgkmcnt(5)
	v_mfma_f32_32x32x16_bf16 v[114:129], v[42:45], v[146:149], v[114:129]
	v_cvt_pk_bf16_f32 v34, v82, v195
	v_cvt_pk_bf16_f32 v35, v84, v196
	v_cvt_pk_bf16_f32 v36, v83, v85
	v_cvt_pk_bf16_f32 v37, v86, v87
	s_waitcnt lgkmcnt(4)
	v_mfma_f32_32x32x16_bf16 v[98:113], v[46:49], v[146:149], v[98:113]
	v_exp_f32_e32 v96, v66
	v_exp_f32_e32 v97, v67
	v_exp_f32_e32 v197, v68
	v_exp_f32_e32 v198, v69
	ds_read_b128 v[38:41], v184 offset:0x3480
	ds_read_b128 v[66:69], v184 offset:0x4e80
	ds_read_b128 v[212:215], v184 offset:0x34a0
	ds_read_b128 v[216:219], v184 offset:0x4ea0
	s_waitcnt lgkmcnt(4)
	v_mfma_f32_32x32x16_bf16 v[114:129], v[170:173], v[142:145], v[114:129]
	v_exp_f32_e32 v199, v70
	v_exp_f32_e32 v200, v71
	v_exp_f32_e32 v201, v72
	v_exp_f32_e32 v202, v73
	v_mfma_f32_32x32x16_bf16 v[98:113], v[174:177], v[142:145], v[98:113]
	v_cvt_pk_bf16_f32 v42, v88, v89
	v_cvt_pk_bf16_f32 v43, v90, v91
	v_cvt_pk_bf16_f32 v44, v92, v93
	v_cvt_pk_bf16_f32 v45, v94, v95
	v_mfma_f32_32x32x16_bf16 v[114:129], v[204:207], v[138:141], v[114:129]
	v_exp_f32_e32 v203, v74
	v_exp_f32_e32 v204, v75
	v_exp_f32_e32 v205, v76
	v_exp_f32_e32 v206, v77
	v_mfma_f32_32x32x16_bf16 v[98:113], v[208:211], v[138:141], v[98:113]
	v_exp_f32_e32 v207, v78
	v_exp_f32_e32 v208, v79
	v_exp_f32_e32 v209, v80
	v_exp_f32_e32 v210, v81
	s_waitcnt lgkmcnt(0)
	s_nop 0
	v_mfma_f32_32x32x16_bf16 v[114:129], v[38:41], v[134:137], v[114:129]
	v_cvt_pk_bf16_f32 v46, v96, v97
	v_cvt_pk_bf16_f32 v47, v197, v198
	v_cvt_pk_bf16_f32 v48, v199, v200
	v_cvt_pk_bf16_f32 v49, v201, v202
	v_mfma_f32_32x32x16_bf16 v[98:113], v[66:69], v[134:137], v[98:113]
	v_mfma_f32_32x32x16_bf16 v[114:129], v[212:215], v[130:133], v[114:129]
	v_cvt_pk_bf16_f32 v38, v203, v204
	v_cvt_pk_bf16_f32 v39, v205, v206
	v_cvt_pk_bf16_f32 v40, v207, v208
	v_cvt_pk_bf16_f32 v41, v209, v210
	ds_read_b64_tr_b16 v[78:79], v0 offset:0
	ds_read_b64_tr_b16 v[80:81], v0 offset:0x400
	ds_read_b64_tr_b16 v[74:75], v0 offset:0x200
	v_mfma_f32_32x32x16_bf16 v[98:113], v[216:219], v[130:133], v[98:113]
	ds_read_b64_tr_b16 v[76:77], v0 offset:0x600
	ds_read_b64_tr_b16 v[70:71], v0 offset:0x800
	ds_read_b64_tr_b16 v[72:73], v0 offset:0xc00
	ds_read_b64_tr_b16 v[66:67], v0 offset:0xa00
	ds_read_b64_tr_b16 v[68:69], v0 offset:0xe00
	s_add_i32 s18, s52, 0xffffe000
	buffer_load_dwordx4 v[170:173], v185, s[64:67], s18 offen
	buffer_load_dwordx4 v[174:177], v185, s[44:47], s18 offen
	s_waitcnt lgkmcnt(0)
	ds_read_b64_tr_b16 v[212:213], v0 offset:0x1000
	ds_read_b64_tr_b16 v[214:215], v0 offset:0x1400
	ds_read_b64_tr_b16 v[216:217], v0 offset:0x1200
	ds_read_b64_tr_b16 v[218:219], v0 offset:0x1600
	ds_read_b64_tr_b16 v[220:221], v0 offset:0x1800
	ds_read_b64_tr_b16 v[222:223], v0 offset:0x1c00
	ds_read_b64_tr_b16 v[228:229], v0 offset:0x1a00
	ds_read_b64_tr_b16 v[230:231], v0 offset:0x1e00
	v_mfma_f32_32x32x16_bf16 v[18:33], v[34:37], v[78:81], v[18:33]
	v_add_f32_e32 v238, v82, v195
	v_add_f32_e32 v239, v84, v196
	v_add_f32_e32 v240, v83, v85
	v_add_f32_e32 v241, v86, v87
	v_add_f32_e32 v238, v238, v239
	v_add_f32_e32 v240, v240, v241
	v_mfma_f32_32x32x16_bf16 v[2:17], v[34:37], v[74:77], v[2:17]
	v_max_f32_e32 v34, v114, v115
	v_max3_f32 v35, v116, v117, v99
	v_max3_f32 v34, v34, v98, v100
	v_max3_f32 v35, v35, v118, v119
	v_mfma_f32_32x32x16_bf16 v[18:33], v[42:45], v[70:73], v[18:33]
	v_max3_f32 v34, v34, v101, v120
	v_max3_f32 v35, v35, v102, v103
	v_add_f32_e32 v238, v240, v238
	v_add_f32_e32 v239, v88, v89
	v_add_f32_e32 v241, v90, v91
	v_mfma_f32_32x32x16_bf16 v[2:17], v[42:45], v[66:69], v[2:17]
	v_max3_f32 v34, v34, v121, v104
	v_max3_f32 v34, v34, v105, v124
	v_max3_f32 v35, v35, v122, v123
	v_add_f32_e32 v239, v239, v241
	v_add_f32_e32 v240, v92, v93
	v_add_f32_e32 v241, v94, v95
	s_waitcnt lgkmcnt(0)
	v_mfma_f32_32x32x16_bf16 v[18:33], v[46:49], v[212:215], v[18:33]
	v_max3_f32 v34, v34, v125, v108
	v_max3_f32 v35, v35, v106, v107
	v_add_f32_e32 v238, v239, v238
	v_add_f32_e32 v240, v240, v241
	s_waitcnt vmcnt(3)
	v_add_u32_e32 v67, s69, v187
	ds_write_b128 v67, v[162:165]
	v_mfma_f32_32x32x16_bf16 v[2:17], v[46:49], v[216:219], v[2:17]
	v_max3_f32 v34, v34, v109, v128
	v_max3_f32 v35, v35, v126, v127
	v_add_f32_e32 v238, v240, v238
	v_add_f32_e32 v239, v96, v97
	v_add_f32_e32 v241, v197, v198
	s_waitcnt vmcnt(2)
	ds_write_b128 v188, v[166:169] offset:24576
	v_mfma_f32_32x32x16_bf16 v[18:33], v[38:41], v[220:223], v[18:33]
	v_max3_f32 v34, v34, v129, v112
	v_max3_f32 v35, v35, v110, v111
	v_add_f32_e32 v239, v239, v241
	v_add_f32_e32 v240, v199, v200
	v_add_f32_e32 v241, v201, v202
	v_add_f32_e32 v238, v239, v238
	v_add_f32_e32 v240, v240, v241
	v_mfma_f32_32x32x16_bf16 v[2:17], v[38:41], v[228:231], v[2:17]
	v_max3_f32 v34, v34, v113, v35
	v_cmp_lt_f32_e32 vcc, s35, v34
	v_add_f32_e32 v238, v240, v238
	v_add_f32_e32 v239, v203, v204
	v_add_f32_e32 v241, v205, v206
	v_add_f32_e32 v239, v239, v241
	v_add_f32_e32 v240, v207, v208
	v_add_f32_e32 v241, v209, v210
	v_add_f32_e32 v238, v239, v238
	v_add_f32_e32 v240, v240, v241
	v_add_f32_e32 v238, v240, v238
	v_add_f32_e32 v194, v194, v238
	s_cbranch_vccnz .Lmy_y272
; #define SBAR() __builtin_amdgcn_sched_barrier(0)
; #define MF(A, B, C) __builtin_amdgcn_mfma_f32_32x32x16_bf16(A, B, C, 0, 0, 0)
; template <int KB, bool HASY>
; __device__ __forceinline__ void phaseA(f32x16& X0, f32x16& X1, f32x16& Y0, f32x16& Y1, bf16x8& pa0, bf16x8& pa1, bf16x8& pa2, bf16x8& pa3,
;                                        const bf16x8* qr, const f32x16& negm, int kaddr, VFr& vf, int vb, float& l_reg) {
;   SBAR();
;   float ls = 0.f;
;   bf16x8 k0 = rd128<KOFF(KB, 0, 0)>(kaddr), k1 = rd128<KOFF(KB, 1, 0)>(kaddr), k2 = rd128<KOFF(KB, 0, 1)>(kaddr), k3 = rd128<KOFF(KB, 1, 1)>(kaddr);
;   if (HASY) { EXP4(Y0, 0); EXP4(Y0, 4); }
;   SBAR(); WAIT4(k0, k1, k2, k3);
;   bf16x8 k4 = rd128<KOFF(KB, 0, 2)>(kaddr), k5 = rd128<KOFF(KB, 1, 2)>(kaddr), k6 = rd128<KOFF(KB, 0, 3)>(kaddr), k7 = rd128<KOFF(KB, 1, 3)>(kaddr);
;   SBAR();
;   X0 = MF(k0, qr[0], negm); if (HASY) { EXP4(Y0, 8); SUM4(Y0, 0); } SBAR();
;   X1 = MF(k1, qr[0], negm); if (HASY) { EXP4(Y0, 12); SUM4(Y0, 4); } SBAR();
;   X0 = MF(k2, qr[1], X0); if (HASY) { PACK8(Y0, 0, pa0); } SBAR();
;   X1 = MF(k3, qr[1], X1); if (HASY) { EXP4(Y1, 0); SUM4(Y0, 8); } SBAR();
;   WAIT4(k4, k5, k6, k7);
;   bf16x8 k8 = rd128<KOFF(KB, 0, 4)>(kaddr), k9 = rd128<KOFF(KB, 1, 4)>(kaddr), k10 = rd128<KOFF(KB, 0, 5)>(kaddr), k11 = rd128<KOFF(KB, 1, 5)>(kaddr);
;   SBAR();
;   X0 = MF(k4, qr[2], X0); if (HASY) { EXP4(Y1, 4); SUM4(Y0, 12); } SBAR();
;   X1 = MF(k5, qr[2], X1); if (HASY) { PACK8(Y0, 8, pa1); } SBAR();
;   X0 = MF(k6, qr[3], X0); if (HASY) { EXP4(Y1, 8); SUM4(Y1, 0); } SBAR();
;   X1 = MF(k7, qr[3], X1); if (HASY) { EXP4(Y1, 12); SUM4(Y1, 4); } SBAR();
;   WAIT4(k8, k9, k10, k11);
;   SBAR();
;   X0 = MF(k8, qr[4], X0); if (HASY) { PACK8(Y1, 0, pa2); } SBAR();
;   X1 = MF(k9, qr[4], X1); if (HASY) { SUM4(Y1, 8); SUM4(Y1, 12); } SBAR();
;   X0 = MF(k10, qr[5], X0); if (HASY) { PACK8(Y1, 8, pa3); } SBAR();
;   X1 = MF(k11, qr[5], X1); if (HASY) vfr_issue<0>(vf, vb);
; __device__ __forceinline__ void attn_unit(const bf16_t* __restrict__ Qb, const bf16_t* __restrict__ KNh, const bf16_t* __restrict__ KRb, const bf16_t* __restrict__ Vh,
;                                           bf16_t* __restrict__ Ob, int nkeys, char* lds, int tid_in) {
;     ...
;     phaseA<0, true>(pA0, pA1, pB0, pB1, pa0, pa1, pa2, pa3, qr, negm, kaddr, vf, vb0 + vprev, l_reg);
;     if (j + 3 < NT) SLOAD(SE, (j + 3) * KVBLK); SBAR();
.Lmy_y259:
	v_add_u32_e32 v237, s76, v192
	s_waitcnt lgkmcnt(0)
	s_barrier
	ds_read_b128 v[66:69], v184 offset:0
	ds_read_b128 v[212:215], v184 offset:0x1a00
	ds_read_b128 v[216:219], v184 offset:32
	v_exp_f32_e32 v195, v114
	v_exp_f32_e32 v197, v115
	v_exp_f32_e32 v198, v116
	v_exp_f32_e32 v201, v117
	v_exp_f32_e32 v196, v118
	v_exp_f32_e32 v199, v119
	v_exp_f32_e32 v200, v120
	v_exp_f32_e32 v202, v121
	ds_read_b128 v[118:121], v184 offset:0x1a20
	ds_read_b128 v[220:223], v184 offset:64
	ds_read_b128 v[228:231], v184 offset:0x1a40
	ds_read_b128 v[238:241], v184 offset:0x60
	ds_read_b128 v[242:245], v184 offset:0x1a60
	s_waitcnt lgkmcnt(7)
	v_mfma_f32_32x32x16_bf16 v[82:97], v[66:69], v[150:153], v[50:65]
	v_exp_f32_e32 v203, v122
	v_exp_f32_e32 v204, v123
	v_exp_f32_e32 v205, v124
	v_exp_f32_e32 v206, v125
	s_waitcnt lgkmcnt(6)
	v_mfma_f32_32x32x16_bf16 v[66:81], v[212:215], v[150:153], v[50:65]
	v_exp_f32_e32 v207, v126
	v_exp_f32_e32 v208, v127
	v_exp_f32_e32 v209, v128
	v_exp_f32_e32 v210, v129
	s_waitcnt lgkmcnt(5)
	v_mfma_f32_32x32x16_bf16 v[82:97], v[216:219], v[146:149], v[82:97]
	v_cvt_pk_bf16_f32 v114, v195, v197
	v_cvt_pk_bf16_f32 v115, v198, v201
	v_cvt_pk_bf16_f32 v116, v196, v199
	v_cvt_pk_bf16_f32 v117, v200, v202
	s_waitcnt lgkmcnt(4)
	v_mfma_f32_32x32x16_bf16 v[66:81], v[118:121], v[146:149], v[66:81]
	v_exp_f32_e32 v211, v98
	v_exp_f32_e32 v212, v99
	v_exp_f32_e32 v213, v100
	v_exp_f32_e32 v214, v101
	ds_read_b128 v[98:101], v184 offset:0x80
	ds_read_b128 v[118:121], v184 offset:0x1a80
	ds_read_b128 v[122:125], v184 offset:0xa0
	ds_read_b128 v[246:249], v184 offset:0x1aa0
	s_waitcnt lgkmcnt(4)
	v_mfma_f32_32x32x16_bf16 v[82:97], v[220:223], v[142:145], v[82:97]
	v_exp_f32_e32 v215, v102
	v_exp_f32_e32 v216, v103
	v_exp_f32_e32 v217, v104
	v_exp_f32_e32 v218, v105
	v_mfma_f32_32x32x16_bf16 v[66:81], v[228:231], v[142:145], v[66:81]
	v_cvt_pk_bf16_f32 v102, v203, v204
	v_cvt_pk_bf16_f32 v103, v205, v206
	v_cvt_pk_bf16_f32 v104, v207, v208
	v_cvt_pk_bf16_f32 v105, v209, v210
	v_mfma_f32_32x32x16_bf16 v[82:97], v[238:241], v[138:141], v[82:97]
	v_exp_f32_e32 v219, v106
	v_exp_f32_e32 v220, v107
	v_exp_f32_e32 v221, v108
	v_exp_f32_e32 v222, v109
	v_mfma_f32_32x32x16_bf16 v[66:81], v[242:245], v[138:141], v[66:81]
	v_exp_f32_e32 v223, v110
	v_exp_f32_e32 v234, v111
	v_exp_f32_e32 v235, v112
	v_exp_f32_e32 v236, v113
	s_waitcnt lgkmcnt(0)
	s_nop 0
	v_mfma_f32_32x32x16_bf16 v[82:97], v[98:101], v[134:137], v[82:97]
	v_cvt_pk_bf16_f32 v106, v211, v212
	v_cvt_pk_bf16_f32 v107, v213, v214
	v_cvt_pk_bf16_f32 v108, v215, v216
	v_cvt_pk_bf16_f32 v109, v217, v218
	v_mfma_f32_32x32x16_bf16 v[66:81], v[118:121], v[134:137], v[66:81]
	v_mfma_f32_32x32x16_bf16 v[82:97], v[122:125], v[130:133], v[82:97]
	v_cvt_pk_bf16_f32 v98, v219, v220
	v_cvt_pk_bf16_f32 v99, v221, v222
	v_cvt_pk_bf16_f32 v100, v223, v234
	v_cvt_pk_bf16_f32 v101, v235, v236
	ds_read_b64_tr_b16 v[126:127], v237 offset:0
	ds_read_b64_tr_b16 v[128:129], v237 offset:0x400
	ds_read_b64_tr_b16 v[122:123], v237 offset:0x200
	v_mfma_f32_32x32x16_bf16 v[66:81], v[246:249], v[130:133], v[66:81]
	ds_read_b64_tr_b16 v[124:125], v237 offset:0x600
	ds_read_b64_tr_b16 v[118:119], v237 offset:0x800
	ds_read_b64_tr_b16 v[120:121], v237 offset:0xc00
	ds_read_b64_tr_b16 v[110:111], v237 offset:0xa00
	ds_read_b64_tr_b16 v[112:113], v237 offset:0xe00
	s_cmp_ge_u32 s39, s38
	s_cselect_b64 s[18:19], -1, 0
	s_and_b64 vcc, exec, s[18:19]
	s_cbranch_vccnz .Lmy_y263
	buffer_load_dwordx4 v[162:165], v185, s[64:67], s52 offen
	buffer_load_dwordx4 v[166:169], v185, s[44:47], s52 offen

; #define LAS __attribute__((address_space(3)))
; #define LDS_WAIT() asm volatile("s_waitcnt lgkmcnt(0)" ::: "memory")
; __device__ __forceinline__ void transpose_item(const float* W, int K, int N, bf16_t* WT, const float* kscale, int mode, LAS float* scr, int item, int lane) {
;     const int nblk = N / 32, kb = item / nblk, nb = item % nblk, k0 = 64 * kb, n0 = 32 * nb;
; #pragma unroll 8
;     for (int i = 0; i < 32; ++i) { const int kk = 2 * i + (lane >> 5); float w = W[(size_t)(k0 + kk) * N + n0 + (lane & 31)]; if (kscale) w *= kscale[k0 + kk]; scr[kk * 33 + (lane & 31)] = w; }
;     LDS_WAIT(); asm volatile("" ::: "memory");
; __device__ __forceinline__ void phase_prologue(const Ctx& F) {
;     ...
;         if (r < I_UKV) { transpose_item(F.in[12] + (size_t)l * 256 * 1024, 256, 1024, (bf16_t*)(F.ws + WS_WUKV) + (size_t)l * 1024 * 256, F.in[11] + l * 256, 0, scr, r, F.lane); continue; } r -= I_UKV;
.LBB0_630:
	v_cndmask_b32_e64 v27, 0, 1, s[28:29]
	v_cmp_ne_u32_e64 s[40:41], 1, v27
	v_lshl_add_u64 v[50:51], v[48:49], 0, s[22:23]
	global_load_dword v106, v[50:51], off
	v_lshl_add_u64 v[66:67], v[44:45], 0, s[22:23]
	global_load_dword v107, v[66:67], off
	v_lshl_add_u64 v[50:51], v[42:43], 0, s[22:23]
	global_load_dword v108, v[50:51], off
	v_lshl_add_u64 v[66:67], v[40:41], 0, s[22:23]
	global_load_dword v109, v[66:67], off
	v_lshl_add_u64 v[50:51], v[38:39], 0, s[22:23]
	global_load_dword v110, v[50:51], off
	v_lshl_add_u64 v[66:67], v[36:37], 0, s[22:23]
	global_load_dword v111, v[66:67], off
	v_lshl_add_u64 v[50:51], v[34:35], 0, s[22:23]
	global_load_dword v112, v[50:51], off
	v_lshl_add_u64 v[66:67], v[2:3], 0, s[22:23]
	global_load_dword v113, v[66:67], off
	s_andn2_b64 vcc, exec, s[28:29]
	s_cbranch_vccnz .Lmy_t1nok
	v_lshl_add_u64 v[50:51], v[46:47], 0, s[30:31]
	global_load_dword v114, v[50:51], off
	v_lshl_add_u64 v[50:51], v[4:5], 0, s[30:31]
	global_load_dword v115, v[50:51], off offset:8
	global_load_dword v116, v[50:51], off offset:16
	global_load_dword v117, v[50:51], off offset:24
	global_load_dword v118, v[50:51], off offset:32
	global_load_dword v119, v[50:51], off offset:40
	global_load_dword v120, v[50:51], off offset:48
	global_load_dword v121, v[50:51], off offset:56
	s_waitcnt vmcnt(0)
	v_mul_f32_e32 v106, v106, v114
	v_mul_f32_e32 v107, v107, v115
	v_mul_f32_e32 v108, v108, v116
	v_mul_f32_e32 v109, v109, v117
	v_mul_f32_e32 v110, v110, v118
	v_mul_f32_e32 v111, v111, v119
	v_mul_f32_e32 v112, v112, v120
	v_mul_f32_e32 v113, v113, v121
.Lmy_t1nok:
	s_waitcnt vmcnt(0)
	ds_write_b32 v0, v106
	ds_write_b32 v0, v107 offset:264
	ds_write_b32 v0, v108 offset:528
	ds_write_b32 v0, v109 offset:792
	ds_write_b32 v0, v110 offset:1056
	ds_write_b32 v0, v111 offset:1320
	ds_write_b32 v0, v112 offset:1584
	ds_write_b32 v0, v113 offset:1848
	s_add_u32 s22, s22, 0x10000
	s_addc_u32 s23, s23, 0
	v_add_u32_e32 v0, 0x840, v0
	v_lshl_add_u64 v[4:5], v[4:5], 0, 64
	v_lshl_add_u64 v[46:47], v[46:47], 0, 64
	s_cmp_lg_u32 s22, 0x40000
	s_cbranch_scc1 .LBB0_630
	s_branch .LBB0_646

; #define LAS __attribute__((address_space(3)))
; #define LDS_WAIT() asm volatile("s_waitcnt lgkmcnt(0)" ::: "memory")
; __device__ __forceinline__ void transpose_item(const float* W, int K, int N, bf16_t* WT, const float* kscale, int mode, LAS float* scr, int item, int lane) {
;     const int nblk = N / 32, kb = item / nblk, nb = item % nblk, k0 = 64 * kb, n0 = 32 * nb;
; #pragma unroll 8
;     for (int i = 0; i < 32; ++i) { const int kk = 2 * i + (lane >> 5); float w = W[(size_t)(k0 + kk) * N + n0 + (lane & 31)]; if (kscale) w *= kscale[k0 + kk]; scr[kk * 33 + (lane & 31)] = w; }
;     LDS_WAIT(); asm volatile("" ::: "memory");
; __device__ __forceinline__ void phase_prologue(const Ctx& F) {
;     ...
;         if (r < I_UQ) { transpose_item(F.in[10] + (size_t)l * 384 * 768, 384, 768, (bf16_t*)(F.ws + WS_WUQ) + (size_t)l * 768 * 384, F.in[9] + l * 384, 2, scr, r, F.lane); continue; } r -= I_UQ;
.LBB0_651:
	v_cndmask_b32_e64 v27, 0, 1, s[28:29]
	v_cmp_ne_u32_e64 s[40:41], 1, v27
	v_lshl_add_u64 v[48:49], v[4:5], 0, s[22:23]
	global_load_dword v106, v[48:49], off
	v_lshl_add_u64 v[48:49], v[46:47], 0, s[22:23]
	global_load_dword v107, v[48:49], off
	v_lshl_add_u64 v[48:49], v[44:45], 0, s[22:23]
	global_load_dword v108, v[48:49], off
	v_lshl_add_u64 v[48:49], v[42:43], 0, s[22:23]
	global_load_dword v109, v[48:49], off
	v_lshl_add_u64 v[48:49], v[40:41], 0, s[22:23]
	global_load_dword v110, v[48:49], off
	v_lshl_add_u64 v[48:49], v[38:39], 0, s[22:23]
	global_load_dword v111, v[48:49], off
	v_lshl_add_u64 v[48:49], v[34:35], 0, s[22:23]
	global_load_dword v112, v[48:49], off
	v_lshl_add_u64 v[48:49], v[2:3], 0, s[22:23]
	global_load_dword v113, v[48:49], off
	s_andn2_b64 vcc, exec, s[28:29]
	s_cbranch_vccnz .Lmy_t2nok
	global_load_dword v114, v[36:37], off offset:-56
	global_load_dword v115, v[36:37], off offset:-48
	global_load_dword v116, v[36:37], off offset:-40
	global_load_dword v117, v[36:37], off offset:-32
	global_load_dword v118, v[36:37], off offset:-24
	global_load_dword v119, v[36:37], off offset:-16
	global_load_dword v120, v[36:37], off offset:-8
	global_load_dword v121, v[36:37], off
	s_waitcnt vmcnt(0)
	v_mul_f32_e32 v106, v106, v114
	v_mul_f32_e32 v107, v107, v115
	v_mul_f32_e32 v108, v108, v116
	v_mul_f32_e32 v109, v109, v117
	v_mul_f32_e32 v110, v110, v118
	v_mul_f32_e32 v111, v111, v119
	v_mul_f32_e32 v112, v112, v120
	v_mul_f32_e32 v113, v113, v121
.Lmy_t2nok:
	s_waitcnt vmcnt(0)
	ds_write_b32 v0, v106
	ds_write_b32 v0, v107 offset:264
	ds_write_b32 v0, v108 offset:528
	ds_write_b32 v0, v109 offset:792
	ds_write_b32 v0, v110 offset:1056
	ds_write_b32 v0, v111 offset:1320
	ds_write_b32 v0, v112 offset:1584
	ds_write_b32 v0, v113 offset:1848
	s_add_u32 s22, s22, 0xc000
	s_addc_u32 s23, s23, 0
	v_add_u32_e32 v0, 0x840, v0
	v_lshl_add_u64 v[36:37], v[36:37], 0, 64
	s_cmp_lg_u32 s22, 0x30000
	s_cbranch_scc1 .LBB0_651
	s_branch .LBB0_667
